# attention routine: unit-0 Q loads and first four K-tile LDS-DMAs issued before the rest of the per-call setup
# speedup vs baseline: 1.0032x; 1.0021x over previous
.Lau_entry:
	v_and_b32_e32 v3, 63, v0
	v_lshrrev_b32_e32 v4, 6, v0
	v_readfirstlane_b32 s75, v138
	v_and_b32_e32 v1, 15, v3
	v_readfirstlane_b32 s76, v4
	v_lshrrev_b32_e32 v2, 4, v3
	s_lshl_b32 s76, s76, 11
	s_add_i32 s76, s76, 0x24000
	v_lshl_add_u32 v4, v2, 2, v138
	ds_read2_b32 v[10:11], v4 offset0:0 offset1:4
	ds_read2_b32 v[12:13], v4 offset0:8 offset1:12
	ds_read2_b32 v[14:15], v4 offset0:16 offset1:20
	ds_read2_b32 v[16:17], v4 offset0:24 offset1:28
	ds_read2_b32 v[18:19], v4 offset0:32 offset1:36
	ds_read2_b32 v[20:21], v4 offset0:40 offset1:44
	ds_read2_b32 v[22:23], v4 offset0:48 offset1:52
	ds_read2_b32 v[24:25], v4 offset0:56 offset1:60
	ds_read2_b32 v[26:27], v4 offset0:64 offset1:68
	ds_read2_b32 v[28:29], v4 offset0:72 offset1:76
	ds_read2_b32 v[30:31], v4 offset0:80 offset1:84
	ds_read2_b32 v[32:33], v4 offset0:88 offset1:92
	ds_read2_b32 v[34:35], v4 offset0:96 offset1:100
	ds_read2_b32 v[36:37], v4 offset0:104 offset1:108
	ds_read2_b32 v[38:39], v4 offset0:112 offset1:116
	ds_read2_b32 v[40:41], v4 offset0:120 offset1:124
	ds_read2_b32 v[42:43], v4 offset0:128 offset1:132
	ds_read2_b32 v[44:45], v4 offset0:136 offset1:140
	ds_read2_b32 v[46:47], v4 offset0:144 offset1:148
	ds_read2_b32 v[48:49], v4 offset0:152 offset1:156
	ds_read2_b32 v[50:51], v4 offset0:160 offset1:164
	ds_read2_b32 v[52:53], v4 offset0:168 offset1:172
	ds_read2_b32 v[54:55], v4 offset0:176 offset1:180
	ds_read2_b32 v[56:57], v4 offset0:184 offset1:188
	ds_read2_b32 v[58:59], v4 offset0:192 offset1:196
	ds_read2_b32 v[60:61], v4 offset0:200 offset1:204
	ds_read2_b32 v[62:63], v4 offset0:208 offset1:212
	ds_read2_b32 v[64:65], v4 offset0:216 offset1:220
	ds_read2_b32 v[66:67], v4 offset0:224 offset1:228
	ds_read2_b32 v[68:69], v4 offset0:232 offset1:236
	ds_read2_b32 v[70:71], v4 offset0:240 offset1:244
	ds_read2_b32 v[72:73], v4 offset0:248 offset1:252
	v_readlane_b32 s40, v251, 27
	v_readlane_b32 s41, v251, 28
	v_readlane_b32 s42, v251, 29
	v_readlane_b32 s43, v251, 30
	v_readlane_b32 s44, v251, 31
	v_readlane_b32 s45, v251, 32
	v_readlane_b32 s46, v251, 49
	v_readlane_b32 s47, v251, 50
	s_lshl_b32 s8, s70, 11
	s_lshl_b32 s9, s72, 9
	s_add_u32 s56, s40, s8
	s_addc_u32 s57, s41, 0
	s_add_u32 s50, s42, s9
	s_addc_u32 s51, s43, 0
	s_add_u32 s52, s44, s9
	s_addc_u32 s53, s45, 0
	s_add_u32 s58, s46, s8
	s_addc_u32 s59, s47, 0
	v_lshlrev_b32_e32 v5, 1, v2
	v_xor_b32_e32 v5, v1, v5
	v_lshlrev_b32_e32 v5, 4, v5
	v_xor_b32_e32 v6, 0x80, v5
	v_and_b32_e32 v7, 3, v1
	v_lshlrev_b32_e32 v9, 4, v2
	v_lshl_add_u32 v91, v7, 8, v9
	s_add_u32 s0, s50, 0
	s_addc_u32 s1, s51, 0
	s_add_u32 s4, s56, 0
	s_addc_u32 s5, s57, 0
	global_load_dwordx4 v[92:95], v91, s[4:5] offset:0
	global_load_dwordx4 v[96:99], v91, s[4:5] offset:64
	global_load_dwordx4 v[100:103], v91, s[4:5] offset:128
	global_load_dwordx4 v[104:107], v91, s[4:5] offset:192
	s_waitcnt lgkmcnt(15)
	v_lshl_add_u32 v10, v10, 9, v5
	v_lshl_add_u32 v11, v11, 9, v5
	v_lshl_add_u32 v12, v12, 9, v6
	v_lshl_add_u32 v13, v13, 9, v6
	v_lshl_add_u32 v14, v14, 9, v5
	v_lshl_add_u32 v15, v15, 9, v5
	v_lshl_add_u32 v16, v16, 9, v6
	v_lshl_add_u32 v17, v17, 9, v6
	v_lshl_add_u32 v18, v18, 9, v5
	v_lshl_add_u32 v19, v19, 9, v5
	v_lshl_add_u32 v20, v20, 9, v6
	v_lshl_add_u32 v21, v21, 9, v6
	v_lshl_add_u32 v22, v22, 9, v5
	v_lshl_add_u32 v23, v23, 9, v5
	v_lshl_add_u32 v24, v24, 9, v6
	v_lshl_add_u32 v25, v25, 9, v6
	s_add_i32 m0, s75, 0x2400
	s_nop 0
	global_load_lds_dwordx4 v10, s[0:1]
	s_add_i32 m0, s75, 0x2800
	s_nop 0
	global_load_lds_dwordx4 v11, s[0:1]
	s_add_i32 m0, s75, 0x2c00
	s_nop 0
	global_load_lds_dwordx4 v12, s[0:1]
	s_add_i32 m0, s75, 0x3000
	s_nop 0
	global_load_lds_dwordx4 v13, s[0:1]
	s_add_i32 m0, s75, 0x3400
	s_nop 0
	global_load_lds_dwordx4 v14, s[0:1]
	s_add_i32 m0, s75, 0x3800
	s_nop 0
	global_load_lds_dwordx4 v15, s[0:1]
	s_add_i32 m0, s75, 0x3c00
	s_nop 0
	global_load_lds_dwordx4 v16, s[0:1]
	s_add_i32 m0, s75, 0x4000
	s_nop 0
	global_load_lds_dwordx4 v17, s[0:1]
	s_add_i32 m0, s75, 0x1400
	s_nop 0
	global_load_lds_dwordx4 v18, s[0:1]
	s_add_i32 m0, s75, 0x1800
	s_nop 0
	global_load_lds_dwordx4 v19, s[0:1]
	s_add_i32 m0, s75, 0x1c00
	s_nop 0
	global_load_lds_dwordx4 v20, s[0:1]
	s_add_i32 m0, s75, 0x2000
	s_nop 0
	global_load_lds_dwordx4 v21, s[0:1]
	s_add_i32 m0, s75, 0x400
	s_nop 0
	global_load_lds_dwordx4 v22, s[0:1]
	s_add_i32 m0, s75, 0x800
	s_nop 0
	global_load_lds_dwordx4 v23, s[0:1]
	s_add_i32 m0, s75, 0xc00
	s_nop 0
	global_load_lds_dwordx4 v24, s[0:1]
	s_add_i32 m0, s75, 0x1000
	s_nop 0
	global_load_lds_dwordx4 v25, s[0:1]
	v_lshlrev_b32_e32 v5, 1, v2
	v_xor_b32_e32 v5, v1, v5
	v_lshlrev_b32_e32 v5, 4, v5
	v_xor_b32_e32 v6, 0x80, v5
	v_and_b32_e32 v7, 3, v1
	v_and_b32_e32 v8, 8, v1
	v_lshl_or_b32 v8, v7, 1, v8
	v_or_b32_e32 v9, 0, v2
	v_xor_b32_e32 v9, v9, v8
	v_lshlrev_b32_e32 v9, 4, v9
	v_lshl_add_u32 v9, v1, 8, v9
	v_add_u32_e32 v74, s75, v9
	v_or_b32_e32 v9, 4, v2
	v_xor_b32_e32 v9, v9, v8
	v_lshlrev_b32_e32 v9, 4, v9
	v_lshl_add_u32 v9, v1, 8, v9
	v_add_u32_e32 v75, s75, v9
	v_or_b32_e32 v9, 8, v2
	v_xor_b32_e32 v9, v9, v8
	v_lshlrev_b32_e32 v9, 4, v9
	v_lshl_add_u32 v9, v1, 8, v9
	v_add_u32_e32 v76, s75, v9
	v_or_b32_e32 v9, 12, v2
	v_xor_b32_e32 v9, v9, v8
	v_lshlrev_b32_e32 v9, 4, v9
	v_lshl_add_u32 v9, v1, 8, v9
	v_add_u32_e32 v77, s75, v9
	v_lshrrev_b32_e32 v128, 2, v1
	v_lshl_or_b32 v129, v2, 3, v128
	v_and_b32_e32 v130, 1, v2
	v_lshl_or_b32 v130, v130, 2, v128
	v_lshlrev_b32_e32 v129, 8, v129
	v_lshl_add_u32 v129, v7, 3, v129
	v_add_u32_e32 v129, s75, v129
	v_xor_b32_e32 v9, 0, v130
	v_lshl_add_u32 v78, v9, 5, v129
	v_xor_b32_e32 v9, 1, v130
	v_lshl_add_u32 v79, v9, 5, v129
	v_xor_b32_e32 v9, 2, v130
	v_lshl_add_u32 v80, v9, 5, v129
	v_xor_b32_e32 v9, 3, v130
	v_lshl_add_u32 v81, v9, 5, v129
	v_xor_b32_e32 v9, 4, v130
	v_lshl_add_u32 v82, v9, 5, v129
	v_xor_b32_e32 v9, 5, v130
	v_lshl_add_u32 v83, v9, 5, v129
	v_xor_b32_e32 v9, 6, v130
	v_lshl_add_u32 v84, v9, 5, v129
	v_xor_b32_e32 v9, 7, v130
	v_lshl_add_u32 v85, v9, 5, v129
	v_lshl_add_u32 v86, v1, 4, s75
	v_lshl_add_u32 v87, v3, 4, s75
	v_lshl_add_u32 v88, v3, 1, s76
	v_cmp_gt_u32_e64 s[20:21], 4, v1
	v_lshlrev_b32_e32 v9, 4, v2
	v_lshl_add_u32 v128, v7, 9, v9
	v_add_u32_e32 v128, s76, v128
	v_add_u32_e32 v131, 0x22000, v9
	v_cndmask_b32_e64 v89, v131, v128, s[20:21]
	v_lshrrev_b32_e32 v128, 3, v1
	v_add_u32_e32 v128, v128, v1
	v_lshl_add_u32 v132, v128, 4, s75
	v_add_u32_e32 v132, 0x400, v132
	v_and_b32_e32 v128, 3, v3
	v_lshrrev_b32_e32 v129, 2, v3
	v_mul_u32_u24_e32 v131, 0x90, v129
	v_lshl_add_u32 v131, v128, 2, v131
	v_add_u32_e32 v133, s75, v131
	v_add_u32_e32 v133, 0x400, v133
	v_lshlrev_b32_e32 v129, 4, v129
	v_lshl_add_u32 v90, v128, 8, v129
	v_lshl_add_u32 v91, v7, 8, v9
	v_mov_b32_e32 v128, 0
	v_mov_b32_e32 v129, 0
	v_lshlrev_b32_e32 v9, 3, v3
	v_add_u32_e32 v9, 0x22000, v9
	ds_write_b64 v9, v[128:129]
	v_cmp_gt_u32_e64 s[24:25], s73, v3
	v_add_u32_e32 v9, 64, v3
	v_cmp_gt_u32_e64 s[26:27], s73, v9
	v_add_u32_e32 v9, 0x80, v3
	v_cmp_gt_u32_e64 s[28:29], s73, v9
	v_add_u32_e32 v9, 0xc0, v3
	v_cmp_gt_u32_e64 s[30:31], s73, v9
	s_waitcnt lgkmcnt(0)
	v_lshl_add_u32 v26, v26, 9, v5
	v_lshl_add_u32 v27, v27, 9, v5
	v_lshl_add_u32 v28, v28, 9, v6
	v_lshl_add_u32 v29, v29, 9, v6
	v_lshl_add_u32 v30, v30, 9, v5
	v_lshl_add_u32 v31, v31, 9, v5
	v_lshl_add_u32 v32, v32, 9, v6
	v_lshl_add_u32 v33, v33, 9, v6
	v_lshl_add_u32 v34, v34, 9, v5
	v_lshl_add_u32 v35, v35, 9, v5
	v_lshl_add_u32 v36, v36, 9, v6
	v_lshl_add_u32 v37, v37, 9, v6
	v_lshl_add_u32 v38, v38, 9, v5
	v_lshl_add_u32 v39, v39, 9, v5
	v_lshl_add_u32 v40, v40, 9, v6
	v_lshl_add_u32 v41, v41, 9, v6
	v_lshl_add_u32 v42, v42, 9, v5
	v_lshl_add_u32 v43, v43, 9, v5
	v_lshl_add_u32 v44, v44, 9, v6
	v_lshl_add_u32 v45, v45, 9, v6
	v_lshl_add_u32 v46, v46, 9, v5
	v_lshl_add_u32 v47, v47, 9, v5
	v_lshl_add_u32 v48, v48, 9, v6
	v_lshl_add_u32 v49, v49, 9, v6
	v_lshl_add_u32 v50, v50, 9, v5
	v_lshl_add_u32 v51, v51, 9, v5
	v_lshl_add_u32 v52, v52, 9, v6
	v_lshl_add_u32 v53, v53, 9, v6
	v_lshl_add_u32 v54, v54, 9, v5
	v_lshl_add_u32 v55, v55, 9, v5
	v_lshl_add_u32 v56, v56, 9, v6
	v_lshl_add_u32 v57, v57, 9, v6
	v_lshl_add_u32 v58, v58, 9, v5
	v_lshl_add_u32 v59, v59, 9, v5
	v_lshl_add_u32 v60, v60, 9, v6
	v_lshl_add_u32 v61, v61, 9, v6
	v_lshl_add_u32 v62, v62, 9, v5
	v_lshl_add_u32 v63, v63, 9, v5
	v_lshl_add_u32 v64, v64, 9, v6
	v_lshl_add_u32 v65, v65, 9, v6
	v_lshl_add_u32 v66, v66, 9, v5
	v_lshl_add_u32 v67, v67, 9, v5
	v_lshl_add_u32 v68, v68, 9, v6
	v_lshl_add_u32 v69, v69, 9, v6
	v_lshl_add_u32 v70, v70, 9, v5
	v_lshl_add_u32 v71, v71, 9, v5
	v_lshl_add_u32 v72, v72, 9, v6
	v_lshl_add_u32 v73, v73, 9, v6
	s_add_u32 s2, s52, 0
	s_addc_u32 s3, s53, 0
	s_add_u32 s6, s58, 0
	s_addc_u32 s7, s59, 0
	s_waitcnt vmcnt(12)
	ds_read_b128 v[108:111], v74 offset:9216
	ds_read_b128 v[112:115], v75 offset:9216
	ds_read_b128 v[116:119], v76 offset:9216
	ds_read_b128 v[120:123], v77 offset:9216
	v_cndmask_b32_e64 v92, 0, v92, s[20:21]
	v_cndmask_b32_e64 v93, 0, v93, s[20:21]
	v_cndmask_b32_e64 v94, 0, v94, s[20:21]
	v_cndmask_b32_e64 v95, 0, v95, s[20:21]
	v_cndmask_b32_e64 v96, 0, v96, s[20:21]
	v_cndmask_b32_e64 v97, 0, v97, s[20:21]
	v_cndmask_b32_e64 v98, 0, v98, s[20:21]
	v_cndmask_b32_e64 v99, 0, v99, s[20:21]
	v_cndmask_b32_e64 v100, 0, v100, s[20:21]
	v_cndmask_b32_e64 v101, 0, v101, s[20:21]
	v_cndmask_b32_e64 v102, 0, v102, s[20:21]
	v_cndmask_b32_e64 v103, 0, v103, s[20:21]
	v_cndmask_b32_e64 v104, 0, v104, s[20:21]
	v_cndmask_b32_e64 v105, 0, v105, s[20:21]
	v_cndmask_b32_e64 v106, 0, v106, s[20:21]
	v_cndmask_b32_e64 v107, 0, v107, s[20:21]
	s_waitcnt lgkmcnt(0)
	v_mfma_f32_16x16x32_bf16 v[140:143], v[92:95], v[108:111], 0
	s_add_i32 m0, s75, 0x2400
	v_mfma_f32_16x16x32_bf16 v[140:143], v[96:99], v[112:115], v[140:143]
	global_load_lds_dwordx4 v26, s[0:1]
	s_add_i32 m0, s75, 0x2800
	v_mfma_f32_16x16x32_bf16 v[140:143], v[100:103], v[116:119], v[140:143]
	global_load_lds_dwordx4 v27, s[0:1]
	s_add_i32 m0, s75, 0x2c00
	v_mfma_f32_16x16x32_bf16 v[140:143], v[104:107], v[120:123], v[140:143]
	global_load_lds_dwordx4 v28, s[0:1]
	s_add_i32 m0, s75, 0x3000
	s_nop 0
	global_load_lds_dwordx4 v29, s[0:1]
	s_waitcnt vmcnt(12)
	ds_read_b128 v[108:111], v74 offset:13312
	ds_read_b128 v[112:115], v75 offset:13312
	ds_read_b128 v[116:119], v76 offset:13312
	ds_read_b128 v[120:123], v77 offset:13312
	s_waitcnt lgkmcnt(0)
	v_mfma_f32_16x16x32_bf16 v[144:147], v[92:95], v[108:111], 0
	s_add_i32 m0, s75, 0x3400
	v_mfma_f32_16x16x32_bf16 v[144:147], v[96:99], v[112:115], v[144:147]
	global_load_lds_dwordx4 v30, s[0:1]
	s_add_i32 m0, s75, 0x3800
	v_mfma_f32_16x16x32_bf16 v[144:147], v[100:103], v[116:119], v[144:147]
	global_load_lds_dwordx4 v31, s[0:1]
	s_add_i32 m0, s75, 0x3c00
	v_mfma_f32_16x16x32_bf16 v[144:147], v[104:107], v[120:123], v[144:147]
	global_load_lds_dwordx4 v32, s[0:1]
	s_add_i32 m0, s75, 0x4000
	s_nop 0
	global_load_lds_dwordx4 v33, s[0:1]
	s_waitcnt vmcnt(12)
	ds_read_b128 v[108:111], v74 offset:5120
	ds_read_b128 v[112:115], v75 offset:5120
	ds_read_b128 v[116:119], v76 offset:5120
	ds_read_b128 v[120:123], v77 offset:5120
	s_waitcnt lgkmcnt(0)
	v_mfma_f32_16x16x32_bf16 v[148:151], v[92:95], v[108:111], 0
	s_add_i32 m0, s75, 0x1400
	v_mfma_f32_16x16x32_bf16 v[148:151], v[96:99], v[112:115], v[148:151]
	global_load_lds_dwordx4 v34, s[0:1]
	s_add_i32 m0, s75, 0x1800
	v_mfma_f32_16x16x32_bf16 v[148:151], v[100:103], v[116:119], v[148:151]
	global_load_lds_dwordx4 v35, s[0:1]
	s_add_i32 m0, s75, 0x1c00
	v_mfma_f32_16x16x32_bf16 v[148:151], v[104:107], v[120:123], v[148:151]
	global_load_lds_dwordx4 v36, s[0:1]
	s_add_i32 m0, s75, 0x2000
	s_nop 0
	global_load_lds_dwordx4 v37, s[0:1]
	s_waitcnt vmcnt(12)
	ds_read_b128 v[108:111], v74 offset:1024
	ds_read_b128 v[112:115], v75 offset:1024
	ds_read_b128 v[116:119], v76 offset:1024
	ds_read_b128 v[120:123], v77 offset:1024
	s_waitcnt lgkmcnt(0)
	v_mfma_f32_16x16x32_bf16 v[152:155], v[92:95], v[108:111], 0
	s_add_i32 m0, s75, 0x400
	v_mfma_f32_16x16x32_bf16 v[152:155], v[96:99], v[112:115], v[152:155]
	global_load_lds_dwordx4 v38, s[0:1]
	s_add_i32 m0, s75, 0x800
	v_mfma_f32_16x16x32_bf16 v[152:155], v[100:103], v[116:119], v[152:155]
	global_load_lds_dwordx4 v39, s[0:1]
	s_add_i32 m0, s75, 0xc00
	v_mfma_f32_16x16x32_bf16 v[152:155], v[104:107], v[120:123], v[152:155]
	global_load_lds_dwordx4 v40, s[0:1]
	s_add_i32 m0, s75, 0x1000
	s_nop 0
	global_load_lds_dwordx4 v41, s[0:1]
	s_waitcnt vmcnt(12)
	ds_read_b128 v[108:111], v74 offset:9216
	ds_read_b128 v[112:115], v75 offset:9216
	ds_read_b128 v[116:119], v76 offset:9216
	ds_read_b128 v[120:123], v77 offset:9216
	s_waitcnt lgkmcnt(0)
	v_mfma_f32_16x16x32_bf16 v[156:159], v[92:95], v[108:111], 0
	s_add_i32 m0, s75, 0x2400
	v_mfma_f32_16x16x32_bf16 v[156:159], v[96:99], v[112:115], v[156:159]
	global_load_lds_dwordx4 v42, s[0:1]
	s_add_i32 m0, s75, 0x2800
	v_mfma_f32_16x16x32_bf16 v[156:159], v[100:103], v[116:119], v[156:159]
	global_load_lds_dwordx4 v43, s[0:1]
	s_add_i32 m0, s75, 0x2c00
	v_mfma_f32_16x16x32_bf16 v[156:159], v[104:107], v[120:123], v[156:159]
	global_load_lds_dwordx4 v44, s[0:1]
	s_add_i32 m0, s75, 0x3000
	s_nop 0
	global_load_lds_dwordx4 v45, s[0:1]
	s_waitcnt vmcnt(12)
	ds_read_b128 v[108:111], v74 offset:13312
	ds_read_b128 v[112:115], v75 offset:13312
	ds_read_b128 v[116:119], v76 offset:13312
	ds_read_b128 v[120:123], v77 offset:13312
	s_waitcnt lgkmcnt(0)
	v_mfma_f32_16x16x32_bf16 v[160:163], v[92:95], v[108:111], 0
	s_add_i32 m0, s75, 0x3400
	v_mfma_f32_16x16x32_bf16 v[160:163], v[96:99], v[112:115], v[160:163]
	global_load_lds_dwordx4 v46, s[0:1]
	s_add_i32 m0, s75, 0x3800
	v_mfma_f32_16x16x32_bf16 v[160:163], v[100:103], v[116:119], v[160:163]
	global_load_lds_dwordx4 v47, s[0:1]
	s_add_i32 m0, s75, 0x3c00
	v_mfma_f32_16x16x32_bf16 v[160:163], v[104:107], v[120:123], v[160:163]
	global_load_lds_dwordx4 v48, s[0:1]
	s_add_i32 m0, s75, 0x4000
	s_nop 0
	global_load_lds_dwordx4 v49, s[0:1]
	s_waitcnt vmcnt(12)
	ds_read_b128 v[108:111], v74 offset:5120
	ds_read_b128 v[112:115], v75 offset:5120
	ds_read_b128 v[116:119], v76 offset:5120
	ds_read_b128 v[120:123], v77 offset:5120
	s_waitcnt lgkmcnt(0)
	v_mfma_f32_16x16x32_bf16 v[164:167], v[92:95], v[108:111], 0
	s_add_i32 m0, s75, 0x1400
	v_mfma_f32_16x16x32_bf16 v[164:167], v[96:99], v[112:115], v[164:167]
	global_load_lds_dwordx4 v50, s[0:1]
	s_add_i32 m0, s75, 0x1800
	v_mfma_f32_16x16x32_bf16 v[164:167], v[100:103], v[116:119], v[164:167]
	global_load_lds_dwordx4 v51, s[0:1]
	s_add_i32 m0, s75, 0x1c00
	v_mfma_f32_16x16x32_bf16 v[164:167], v[104:107], v[120:123], v[164:167]
	global_load_lds_dwordx4 v52, s[0:1]
	s_add_i32 m0, s75, 0x2000
	s_nop 0
	global_load_lds_dwordx4 v53, s[0:1]
	s_waitcnt vmcnt(12)
	ds_read_b128 v[108:111], v74 offset:1024
	ds_read_b128 v[112:115], v75 offset:1024
	ds_read_b128 v[116:119], v76 offset:1024
	ds_read_b128 v[120:123], v77 offset:1024
	s_waitcnt lgkmcnt(0)
	v_mfma_f32_16x16x32_bf16 v[168:171], v[92:95], v[108:111], 0
	s_add_i32 m0, s75, 0x400
	v_mfma_f32_16x16x32_bf16 v[168:171], v[96:99], v[112:115], v[168:171]
	global_load_lds_dwordx4 v54, s[0:1]
	s_add_i32 m0, s75, 0x800
	v_mfma_f32_16x16x32_bf16 v[168:171], v[100:103], v[116:119], v[168:171]
	global_load_lds_dwordx4 v55, s[0:1]
	s_add_i32 m0, s75, 0xc00
	v_mfma_f32_16x16x32_bf16 v[168:171], v[104:107], v[120:123], v[168:171]
	global_load_lds_dwordx4 v56, s[0:1]
	s_add_i32 m0, s75, 0x1000
	s_nop 0
	global_load_lds_dwordx4 v57, s[0:1]
	s_waitcnt vmcnt(12)
	ds_read_b128 v[108:111], v74 offset:9216
	ds_read_b128 v[112:115], v75 offset:9216
	ds_read_b128 v[116:119], v76 offset:9216
	ds_read_b128 v[120:123], v77 offset:9216
	s_waitcnt lgkmcnt(0)
	v_mfma_f32_16x16x32_bf16 v[184:187], v[92:95], v[108:111], 0
	s_add_i32 m0, s75, 0x2400
	v_mfma_f32_16x16x32_bf16 v[184:187], v[96:99], v[112:115], v[184:187]
	global_load_lds_dwordx4 v58, s[0:1]
	s_add_i32 m0, s75, 0x2800
	v_mfma_f32_16x16x32_bf16 v[184:187], v[100:103], v[116:119], v[184:187]
	global_load_lds_dwordx4 v59, s[0:1]
	s_add_i32 m0, s75, 0x2c00
	v_mfma_f32_16x16x32_bf16 v[184:187], v[104:107], v[120:123], v[184:187]
	global_load_lds_dwordx4 v60, s[0:1]
	s_add_i32 m0, s75, 0x3000
	s_nop 0
	global_load_lds_dwordx4 v61, s[0:1]
	s_waitcnt vmcnt(12)
	ds_read_b128 v[108:111], v74 offset:13312
	ds_read_b128 v[112:115], v75 offset:13312
	ds_read_b128 v[116:119], v76 offset:13312
	ds_read_b128 v[120:123], v77 offset:13312
	s_waitcnt lgkmcnt(0)
	v_mfma_f32_16x16x32_bf16 v[188:191], v[92:95], v[108:111], 0
	s_add_i32 m0, s75, 0x3400
	v_mfma_f32_16x16x32_bf16 v[188:191], v[96:99], v[112:115], v[188:191]
	global_load_lds_dwordx4 v62, s[0:1]
	s_add_i32 m0, s75, 0x3800
	v_mfma_f32_16x16x32_bf16 v[188:191], v[100:103], v[116:119], v[188:191]
	global_load_lds_dwordx4 v63, s[0:1]
	s_add_i32 m0, s75, 0x3c00
	v_mfma_f32_16x16x32_bf16 v[188:191], v[104:107], v[120:123], v[188:191]
	global_load_lds_dwordx4 v64, s[0:1]
	s_add_i32 m0, s75, 0x4000
	s_nop 0
	global_load_lds_dwordx4 v65, s[0:1]
	s_waitcnt vmcnt(12)
	ds_read_b128 v[108:111], v74 offset:5120
	ds_read_b128 v[112:115], v75 offset:5120
	ds_read_b128 v[116:119], v76 offset:5120
	ds_read_b128 v[120:123], v77 offset:5120
	s_waitcnt lgkmcnt(0)
	v_mfma_f32_16x16x32_bf16 v[192:195], v[92:95], v[108:111], 0
	s_add_i32 m0, s75, 0x1400
	v_mfma_f32_16x16x32_bf16 v[192:195], v[96:99], v[112:115], v[192:195]
	global_load_lds_dwordx4 v66, s[0:1]
	s_add_i32 m0, s75, 0x1800
	v_mfma_f32_16x16x32_bf16 v[192:195], v[100:103], v[116:119], v[192:195]
	global_load_lds_dwordx4 v67, s[0:1]
	s_add_i32 m0, s75, 0x1c00
	v_mfma_f32_16x16x32_bf16 v[192:195], v[104:107], v[120:123], v[192:195]
	global_load_lds_dwordx4 v68, s[0:1]
	s_add_i32 m0, s75, 0x2000
	s_nop 0
	global_load_lds_dwordx4 v69, s[0:1]
	s_waitcnt vmcnt(12)
	ds_read_b128 v[108:111], v74 offset:1024
	ds_read_b128 v[112:115], v75 offset:1024
	ds_read_b128 v[116:119], v76 offset:1024
	ds_read_b128 v[120:123], v77 offset:1024
	s_waitcnt lgkmcnt(0)
	v_mfma_f32_16x16x32_bf16 v[196:199], v[92:95], v[108:111], 0
	s_add_i32 m0, s75, 0x400
	v_mfma_f32_16x16x32_bf16 v[196:199], v[96:99], v[112:115], v[196:199]
	global_load_lds_dwordx4 v70, s[0:1]
	s_add_i32 m0, s75, 0x800
	v_mfma_f32_16x16x32_bf16 v[196:199], v[100:103], v[116:119], v[196:199]
	global_load_lds_dwordx4 v71, s[0:1]
	s_add_i32 m0, s75, 0xc00
	v_mfma_f32_16x16x32_bf16 v[196:199], v[104:107], v[120:123], v[196:199]
	global_load_lds_dwordx4 v72, s[0:1]
	s_add_i32 m0, s75, 0x1000
	s_nop 0
	global_load_lds_dwordx4 v73, s[0:1]
	s_waitcnt vmcnt(12)
	ds_read_b128 v[108:111], v74 offset:9216
	ds_read_b128 v[112:115], v75 offset:9216
	ds_read_b128 v[116:119], v76 offset:9216
	ds_read_b128 v[120:123], v77 offset:9216
	s_waitcnt lgkmcnt(0)
	v_mfma_f32_16x16x32_bf16 v[200:203], v[92:95], v[108:111], 0
	v_mfma_f32_16x16x32_bf16 v[200:203], v[96:99], v[112:115], v[200:203]
	v_mfma_f32_16x16x32_bf16 v[200:203], v[100:103], v[116:119], v[200:203]
	v_mfma_f32_16x16x32_bf16 v[200:203], v[104:107], v[120:123], v[200:203]
	s_waitcnt vmcnt(8)
	ds_read_b128 v[108:111], v74 offset:13312
	ds_read_b128 v[112:115], v75 offset:13312
	ds_read_b128 v[116:119], v76 offset:13312
	ds_read_b128 v[120:123], v77 offset:13312
	s_waitcnt lgkmcnt(0)
	v_mfma_f32_16x16x32_bf16 v[204:207], v[92:95], v[108:111], 0
	v_mfma_f32_16x16x32_bf16 v[204:207], v[96:99], v[112:115], v[204:207]
	v_mfma_f32_16x16x32_bf16 v[204:207], v[100:103], v[116:119], v[204:207]
	v_mfma_f32_16x16x32_bf16 v[204:207], v[104:107], v[120:123], v[204:207]
	s_waitcnt vmcnt(4)
	ds_read_b128 v[108:111], v74 offset:5120
	ds_read_b128 v[112:115], v75 offset:5120
	ds_read_b128 v[116:119], v76 offset:5120
	ds_read_b128 v[120:123], v77 offset:5120
	s_waitcnt lgkmcnt(0)
	v_mfma_f32_16x16x32_bf16 v[208:211], v[92:95], v[108:111], 0
	v_mfma_f32_16x16x32_bf16 v[208:211], v[96:99], v[112:115], v[208:211]
	v_mfma_f32_16x16x32_bf16 v[208:211], v[100:103], v[116:119], v[208:211]
	v_mfma_f32_16x16x32_bf16 v[208:211], v[104:107], v[120:123], v[208:211]
	s_waitcnt vmcnt(0)
	ds_read_b128 v[108:111], v74 offset:1024
	ds_read_b128 v[112:115], v75 offset:1024
	ds_read_b128 v[116:119], v76 offset:1024
	ds_read_b128 v[120:123], v77 offset:1024
	s_waitcnt lgkmcnt(0)
	v_mfma_f32_16x16x32_bf16 v[212:215], v[92:95], v[108:111], 0
	v_mfma_f32_16x16x32_bf16 v[212:215], v[96:99], v[112:115], v[212:215]
	v_mfma_f32_16x16x32_bf16 v[212:215], v[100:103], v[116:119], v[212:215]
	v_mfma_f32_16x16x32_bf16 v[212:215], v[104:107], v[120:123], v[212:215]
	s_nop 7
	s_mov_b64 exec, 0xffff
	ds_write_b128 v86, v[140:143] offset:1024
	ds_write_b128 v86, v[144:147] offset:1280
	ds_write_b128 v86, v[148:151] offset:1536
	ds_write_b128 v86, v[152:155] offset:1792
	ds_write_b128 v86, v[156:159] offset:2048
	ds_write_b128 v86, v[160:163] offset:2304
	ds_write_b128 v86, v[164:167] offset:2560
	ds_write_b128 v86, v[168:171] offset:2816
	ds_write_b128 v86, v[184:187] offset:3072
	ds_write_b128 v86, v[188:191] offset:3328
	ds_write_b128 v86, v[192:195] offset:3584
	ds_write_b128 v86, v[196:199] offset:3840
	ds_write_b128 v86, v[200:203] offset:4096
	ds_write_b128 v86, v[204:207] offset:4352
	ds_write_b128 v86, v[208:211] offset:4608
	ds_write_b128 v86, v[212:215] offset:4864
	s_mov_b64 exec, -1
	s_add_i32 m0, s75, 0x2400
	s_nop 0
	global_load_lds_dwordx4 v10, s[2:3]
	s_add_i32 m0, s75, 0x2800
	s_nop 0
	global_load_lds_dwordx4 v11, s[2:3]
	s_add_i32 m0, s75, 0x2c00
	s_nop 0
	global_load_lds_dwordx4 v12, s[2:3]
	s_add_i32 m0, s75, 0x3000
	s_nop 0
	global_load_lds_dwordx4 v13, s[2:3]
	s_add_i32 m0, s75, 0x3400
	s_nop 0
	global_load_lds_dwordx4 v14, s[2:3]
	s_add_i32 m0, s75, 0x3800
	s_nop 0
	global_load_lds_dwordx4 v15, s[2:3]
	s_add_i32 m0, s75, 0x3c00
	s_nop 0
	global_load_lds_dwordx4 v16, s[2:3]
	s_add_i32 m0, s75, 0x4000
	s_nop 0
	global_load_lds_dwordx4 v17, s[2:3]
	s_waitcnt lgkmcnt(0)
	ds_read_b128 v[108:111], v87 offset:1024
	ds_read_b128 v[112:115], v87 offset:2048
	ds_read_b128 v[116:119], v87 offset:3072
	ds_read_b128 v[120:123], v87 offset:4096
	s_waitcnt lgkmcnt(0)
	s_add_i32 m0, s75, 0x400
	s_nop 0
	global_load_lds_dwordx4 v18, s[2:3]
	s_add_i32 m0, s75, 0x800
	s_nop 0
	global_load_lds_dwordx4 v19, s[2:3]
	s_add_i32 m0, s75, 0xc00
	s_nop 0
	global_load_lds_dwordx4 v20, s[2:3]
	s_add_i32 m0, s75, 0x1000
	s_nop 0
	global_load_lds_dwordx4 v21, s[2:3]
	s_add_i32 m0, s75, 0x1400
	s_nop 0
	global_load_lds_dwordx4 v22, s[2:3]
	s_add_i32 m0, s75, 0x1800
	s_nop 0
	global_load_lds_dwordx4 v23, s[2:3]
	s_add_i32 m0, s75, 0x1c00
	s_nop 0
	global_load_lds_dwordx4 v24, s[2:3]
	s_add_i32 m0, s75, 0x2000
	s_nop 0
	global_load_lds_dwordx4 v25, s[2:3]
	s_cmp_eq_u32 s73, 0x100
	s_cbranch_scc1 .Lau_nomask1_0
	v_mov_b32_e32 v9, 0xff61b1e6
	v_cndmask_b32_e64 v108, v9, v108, s[24:25]
	v_cndmask_b32_e64 v109, v9, v109, s[24:25]
	v_cndmask_b32_e64 v110, v9, v110, s[24:25]
	v_cndmask_b32_e64 v111, v9, v111, s[24:25]
	v_cndmask_b32_e64 v112, v9, v112, s[26:27]
	v_cndmask_b32_e64 v113, v9, v113, s[26:27]
	v_cndmask_b32_e64 v114, v9, v114, s[26:27]
	v_cndmask_b32_e64 v115, v9, v115, s[26:27]
	v_cndmask_b32_e64 v116, v9, v116, s[28:29]
	v_cndmask_b32_e64 v117, v9, v117, s[28:29]
	v_cndmask_b32_e64 v118, v9, v118, s[28:29]
	v_cndmask_b32_e64 v119, v9, v119, s[28:29]
	v_cndmask_b32_e64 v120, v9, v120, s[30:31]
	v_cndmask_b32_e64 v121, v9, v121, s[30:31]
	v_cndmask_b32_e64 v122, v9, v122, s[30:31]
	v_cndmask_b32_e64 v123, v9, v123, s[30:31]
